# attention: the PV-section priority raise moved up before that section's four LDS fragment reads
# speedup vs baseline: 1.0038x; 1.0034x over previous
.Lattn_noresc:
	v_sub_f32_e32 v80, v80, v241
	v_sub_f32_e32 v81, v81, v241
	v_sub_f32_e32 v82, v82, v241
	v_sub_f32_e32 v83, v83, v241
	v_sub_f32_e32 v84, v84, v241
	v_sub_f32_e32 v85, v85, v241
	v_sub_f32_e32 v86, v86, v241
	v_sub_f32_e32 v87, v87, v241
	v_sub_f32_e32 v88, v88, v241
	v_sub_f32_e32 v89, v89, v241
	v_sub_f32_e32 v90, v90, v241
	v_sub_f32_e32 v91, v91, v241
	v_sub_f32_e32 v92, v92, v241
	v_sub_f32_e32 v93, v93, v241
	v_sub_f32_e32 v94, v94, v241
	v_sub_f32_e32 v95, v95, v241
	v_sub_f32_e32 v64, v64, v241
	v_sub_f32_e32 v65, v65, v241
	v_sub_f32_e32 v66, v66, v241
	v_sub_f32_e32 v67, v67, v241
	v_sub_f32_e32 v68, v68, v241
	v_sub_f32_e32 v69, v69, v241
	v_sub_f32_e32 v70, v70, v241
	v_sub_f32_e32 v71, v71, v241
	v_sub_f32_e32 v72, v72, v241
	v_sub_f32_e32 v73, v73, v241
	v_sub_f32_e32 v74, v74, v241
	v_sub_f32_e32 v75, v75, v241
	v_sub_f32_e32 v76, v76, v241
	v_sub_f32_e32 v77, v77, v241
	v_sub_f32_e32 v78, v78, v241
	v_sub_f32_e32 v79, v79, v241
	v_exp_f32_e32 v80, v80
	v_exp_f32_e32 v81, v81
	v_exp_f32_e32 v82, v82
	v_add_f32_e32 v221, v80, v81
	v_exp_f32_e32 v83, v83
	v_add_f32_e32 v221, v221, v82
	v_exp_f32_e32 v84, v84
	v_add_f32_e32 v221, v221, v83
	v_exp_f32_e32 v85, v85
	v_add_f32_e32 v221, v221, v84
	v_exp_f32_e32 v86, v86
	v_add_f32_e32 v221, v221, v85
	v_exp_f32_e32 v87, v87
	v_add_f32_e32 v221, v221, v86
	v_exp_f32_e32 v88, v88
	v_add_f32_e32 v221, v221, v87
	v_exp_f32_e32 v89, v89
	v_add_f32_e32 v221, v221, v88
	v_exp_f32_e32 v90, v90
	v_add_f32_e32 v221, v221, v89
	v_exp_f32_e32 v91, v91
	v_add_f32_e32 v221, v221, v90
	v_exp_f32_e32 v92, v92
	v_add_f32_e32 v221, v221, v91
	v_exp_f32_e32 v93, v93
	v_add_f32_e32 v221, v221, v92
	v_exp_f32_e32 v94, v94
	v_add_f32_e32 v221, v221, v93
	v_exp_f32_e32 v95, v95
	v_add_f32_e32 v221, v221, v94
	v_exp_f32_e32 v64, v64
	v_add_f32_e32 v221, v221, v95
	v_exp_f32_e32 v65, v65
	v_add_f32_e32 v221, v221, v64
	v_exp_f32_e32 v66, v66
	v_add_f32_e32 v221, v221, v65
	v_exp_f32_e32 v67, v67
	v_add_f32_e32 v221, v221, v66
	v_exp_f32_e32 v68, v68
	v_add_f32_e32 v221, v221, v67
	v_exp_f32_e32 v69, v69
	v_add_f32_e32 v221, v221, v68
	v_exp_f32_e32 v70, v70
	v_add_f32_e32 v221, v221, v69
	v_exp_f32_e32 v71, v71
	v_add_f32_e32 v221, v221, v70
	v_exp_f32_e32 v72, v72
	v_add_f32_e32 v221, v221, v71
	v_exp_f32_e32 v73, v73
	v_add_f32_e32 v221, v221, v72
	v_exp_f32_e32 v74, v74
	v_add_f32_e32 v221, v221, v73
	v_exp_f32_e32 v75, v75
	v_add_f32_e32 v221, v221, v74
	v_exp_f32_e32 v76, v76
	v_add_f32_e32 v221, v221, v75
	v_exp_f32_e32 v77, v77
	v_add_f32_e32 v221, v221, v76
	v_exp_f32_e32 v78, v78
	v_add_f32_e32 v221, v221, v77
	v_exp_f32_e32 v79, v79
	v_add_f32_e32 v221, v221, v78
	s_nop 0
	v_add_f32_e32 v221, v221, v79
	v_fmac_f32_e32 v221, v215, v220
	v_cvt_pk_bf16_f32 v80, v80, v81
	v_cvt_pk_bf16_f32 v81, v82, v83
	v_cvt_pk_bf16_f32 v82, v84, v85
	v_cvt_pk_bf16_f32 v83, v86, v87
	v_cvt_pk_bf16_f32 v88, v88, v89
	v_cvt_pk_bf16_f32 v89, v90, v91
	v_cvt_pk_bf16_f32 v90, v92, v93
	v_cvt_pk_bf16_f32 v91, v94, v95
	v_cvt_pk_bf16_f32 v64, v64, v65
	v_cvt_pk_bf16_f32 v65, v66, v67
	v_cvt_pk_bf16_f32 v66, v68, v69
	v_cvt_pk_bf16_f32 v67, v70, v71
	v_cvt_pk_bf16_f32 v72, v72, v73
	v_cvt_pk_bf16_f32 v73, v74, v75
	v_cvt_pk_bf16_f32 v74, v76, v77
	v_cvt_pk_bf16_f32 v75, v78, v79
	v_mov_b32_e32 v215, v221
	v_mov_b32_e32 v240, v241
	s_setprio 1
	ds_read_b128 v[84:87], v239 offset:25632
	ds_read_b128 v[92:95], v239 offset:30240
	ds_read_b128 v[68:71], v239 offset:34848
	ds_read_b128 v[76:79], v239 offset:39456
	s_waitcnt lgkmcnt(7)
	v_mfma_f32_32x32x16_bf16 v[48:63], v[244:247], v[80:83], v[48:63]
	ds_read_b128 v[244:247], v239 offset:25664
	s_waitcnt lgkmcnt(7)
	v_mfma_f32_32x32x16_bf16 v[32:47], v[248:251], v[80:83], v[32:47]
	ds_read_b128 v[248:251], v239 offset:30272
	s_waitcnt lgkmcnt(7)
	v_mfma_f32_32x32x16_bf16 v[16:31], v[222:225], v[80:83], v[16:31]
	ds_read_b128 v[222:225], v239 offset:34880
	s_waitcnt lgkmcnt(7)
	v_mfma_f32_32x32x16_bf16 v[0:15], v[230:233], v[80:83], v[0:15]
	ds_read_b128 v[230:233], v239 offset:39488
	s_waitcnt lgkmcnt(7)
	v_mfma_f32_32x32x16_bf16 v[48:63], v[84:87], v[88:91], v[48:63]
	ds_read_b128 v[84:87], v239 offset:25696
	s_waitcnt lgkmcnt(7)
	v_mfma_f32_32x32x16_bf16 v[32:47], v[92:95], v[88:91], v[32:47]
	ds_read_b128 v[92:95], v239 offset:30304
	s_waitcnt lgkmcnt(7)
	v_mfma_f32_32x32x16_bf16 v[16:31], v[68:71], v[88:91], v[16:31]
	ds_read_b128 v[68:71], v239 offset:34912
	s_waitcnt lgkmcnt(7)
	v_mfma_f32_32x32x16_bf16 v[0:15], v[76:79], v[88:91], v[0:15]
	ds_read_b128 v[76:79], v239 offset:39520
	s_waitcnt lgkmcnt(7)
	v_mfma_f32_32x32x16_bf16 v[48:63], v[244:247], v[64:67], v[48:63]
	s_waitcnt lgkmcnt(6)
	v_mfma_f32_32x32x16_bf16 v[32:47], v[248:251], v[64:67], v[32:47]
	s_waitcnt lgkmcnt(5)
	v_mfma_f32_32x32x16_bf16 v[16:31], v[222:225], v[64:67], v[16:31]
	s_waitcnt lgkmcnt(4)
	v_mfma_f32_32x32x16_bf16 v[0:15], v[230:233], v[64:67], v[0:15]
	s_waitcnt lgkmcnt(3)
	v_mfma_f32_32x32x16_bf16 v[48:63], v[84:87], v[72:75], v[48:63]
	s_waitcnt lgkmcnt(2)
	v_mfma_f32_32x32x16_bf16 v[32:47], v[92:95], v[72:75], v[32:47]
	s_waitcnt lgkmcnt(1)
	v_mfma_f32_32x32x16_bf16 v[16:31], v[68:71], v[72:75], v[16:31]
	s_waitcnt lgkmcnt(0)
	v_mfma_f32_32x32x16_bf16 v[0:15], v[76:79], v[72:75], v[0:15]
	s_getreg_b32 s4, hwreg(HW_REG_HW_ID, 0, 4)
	s_bitcmp1_b32 s4, 0
	s_cbranch_scc1 .Lprio_keep1
	s_setprio 0
